# attention window loop: P.V MFMAs of the first two half-blocks take C from the registers O lives in (C != D), rescale in place: 16 v_mov_b64 per key-block pair removed
# baseline (speedup 1.0000x reference)
.LBB0_245:
	s_nop 0
	v_max3_f32 v8, v0, v1, v2
	v_max3_f32 v91, v4, v5, v6
	v_max3_f32 v91, v91, v7, v3
	v_max_f32_e32 v90, v8, v91
	v_mov_b32_e32 v8, v184
	ds_bpermute_b32 v92, v8, v90
	s_waitcnt lgkmcnt(0)
	v_max_f32_e32 v90, v90, v92
	v_mov_b32_e32 v171, v185
	ds_bpermute_b32 v91, v171, v90
	s_waitcnt lgkmcnt(0)
	v_max_f32_e32 v90, v90, v91
	v_cmp_gt_f32_e32 vcc, v90, v152
	s_cbranch_vccz .LBB0_251
	v_max_f32_e32 v90, v90, v90
	v_max_f32_e32 v91, v152, v152
	v_max_f32_e32 v122, v91, v90
	v_sub_f32_e32 v90, v152, v122
	v_exp_f32_e32 v102, v90
	v_mov_b32_e32 v123, v153
	v_mov_b32_e32 v155, v139
	v_mov_b64_e32 v[152:153], v[122:123]
	v_mul_f32_e32 v154, v138, v102
	v_mul_f32_e32 v40, v40, v102
	v_mul_f32_e32 v41, v41, v102
	v_mul_f32_e32 v38, v38, v102
	v_mul_f32_e32 v39, v39, v102
	v_mul_f32_e32 v36, v36, v102
	v_mul_f32_e32 v37, v37, v102
	v_mul_f32_e32 v34, v34, v102
	v_mul_f32_e32 v35, v35, v102
	v_mul_f32_e32 v32, v32, v102
	v_mul_f32_e32 v33, v33, v102
	v_mul_f32_e32 v30, v30, v102
	v_mul_f32_e32 v31, v31, v102
	v_mul_f32_e32 v28, v28, v102
	v_mul_f32_e32 v29, v29, v102
	v_mul_f32_e32 v27, v27, v102
	v_mul_f32_e32 v26, v26, v102
	s_branch .LBB0_252

.LBB0_251:
	v_mov_b64_e32 v[154:155], v[138:139]
	v_mov_b32_e32 v122, v152
.LBB0_252:
	v_sub_f32_e32 v0, v0, v122
	v_exp_f32_e32 v0, v0
	v_sub_f32_e32 v1, v1, v122
	v_exp_f32_e32 v1, v1
	v_sub_f32_e32 v2, v2, v122
	v_exp_f32_e32 v2, v2
	v_sub_f32_e32 v3, v3, v122
	v_exp_f32_e32 v3, v3
	v_sub_f32_e32 v4, v4, v122
	v_sub_f32_e32 v5, v5, v122
	v_sub_f32_e32 v6, v6, v122
	v_sub_f32_e32 v7, v7, v122
	v_add_f32_e32 v123, 0, v0
	v_exp_f32_e32 v4, v4
	v_exp_f32_e32 v5, v5
	v_exp_f32_e32 v6, v6
	v_exp_f32_e32 v7, v7
	v_add_f32_e32 v123, v1, v123
	v_add_f32_e32 v123, v2, v123
	v_add_f32_e32 v123, v3, v123
	v_add_f32_e32 v123, v4, v123
	v_cvt_pk_bf16_f32 v0, v0, v1
	v_cvt_pk_bf16_f32 v1, v2, v3
	v_cvt_pk_bf16_f32 v2, v4, v5
	v_cvt_pk_bf16_f32 v3, v6, v7
	v_add_f32_e32 v123, v5, v123
	v_add_f32_e32 v123, v6, v123
	s_waitcnt vmcnt(11)
	v_mfma_f32_16x16x32_bf16 v[90:93], v[54:57], v[0:3], v[38:41]
	v_add_f32_e32 v122, v7, v123
	s_or_b64 s[28:29], s[18:19], s[38:39]
	v_add_f32_e32 v154, v154, v122
	s_waitcnt vmcnt(10)
	v_mfma_f32_16x16x32_bf16 v[94:97], v[50:53], v[0:3], v[34:37]
	s_andn2_b64 vcc, exec, s[28:29]
	s_waitcnt vmcnt(9)
	v_mfma_f32_16x16x32_bf16 v[98:101], v[46:49], v[0:3], v[30:33]
	s_waitcnt vmcnt(8)
	v_mfma_f32_16x16x32_bf16 v[102:105], v[42:45], v[0:3], v[26:29]
	s_cbranch_vccnz .LBB0_259
	v_mov_b32_e32 v4, v168
	ds_read_b128 v[0:3], v4
	ds_read_b128 v[122:125], v4 offset:64
	s_mov_b64 s[28:29], -1
	s_and_b64 vcc, exec, s[36:37]
	s_waitcnt lgkmcnt(1)
	v_mfma_f32_16x16x32_bf16 v[4:7], v[82:85], v[0:3], 0
	v_mfma_f32_16x16x32_bf16 v[82:85], v[86:89], v[0:3], 0
	s_waitcnt lgkmcnt(0)
	v_mfma_f32_16x16x32_bf16 v[74:77], v[74:77], v[122:125], v[4:7]
	v_mfma_f32_16x16x32_bf16 v[78:81], v[78:81], v[122:125], v[82:85]
	s_cbranch_vccz .LBB0_255
	v_lshl_add_u32 v0, v170, 2, s26
	v_add_u32_e32 v2, 0x43c, v0
	s_nop 0
	v_add_u32_e32 v4, 0x444, v0
	v_add_u32_e32 v6, 0x44c, v0
	v_add_u32_e32 v0, 0x454, v0
	ds_read2_b32 v[0:1], v0 offset1:1
	ds_read2_b32 v[2:3], v2 offset1:1
	ds_read2_b32 v[4:5], v4 offset1:1
	ds_read2_b32 v[6:7], v6 offset1:1
	s_mov_b32 s2, 0x3e38aa3b
	s_waitcnt lgkmcnt(3)
	v_fma_f32 v82, v80, s2, v0
	v_fma_f32 v83, v81, s2, v1
	s_waitcnt lgkmcnt(2)
	v_fma_f32 v0, v74, s2, v2
	v_fma_f32 v1, v75, s2, v3
	s_waitcnt lgkmcnt(1)
	v_fma_f32 v2, v76, s2, v4
	v_fma_f32 v3, v77, s2, v5
	s_waitcnt lgkmcnt(0)
	v_fma_f32 v4, v78, s2, v6
	v_fma_f32 v5, v79, s2, v7
	v_cndmask_b32_e64 v3, v194, v3, s[0:1]
	v_cndmask_b32_e64 v5, v194, v5, s[94:95]
	v_cndmask_b32_e64 v4, v194, v4, s[96:97]
	v_cndmask_b32_e64 v2, v194, v2, s[4:5]
	v_cndmask_b32_e64 v1, v194, v1, s[6:7]
	v_cndmask_b32_e64 v0, v194, v0, s[88:89]
	v_cndmask_b32_e64 v6, v194, v82, s[92:93]
	v_cndmask_b32_e64 v7, v194, v83, s[90:91]
	s_mov_b64 s[28:29], 0

.LBB0_257:
	s_nop 3
	v_max3_f32 v74, v0, v1, v2
	v_max3_f32 v76, v4, v5, v6
	v_max3_f32 v76, v76, v7, v3
	v_max_f32_e32 v74, v74, v76
	ds_bpermute_b32 v75, v8, v74
	s_waitcnt lgkmcnt(0)
	v_max_f32_e32 v74, v74, v75
	ds_bpermute_b32 v75, v171, v74
	s_waitcnt lgkmcnt(0)
	v_max_f32_e32 v74, v74, v75
	v_cmp_gt_f32_e32 vcc, v74, v153
	s_cbranch_vccz .LBB0_260
	v_max_f32_e32 v74, v74, v74
	v_max_f32_e32 v75, v153, v153
	v_max_f32_e32 v122, v75, v74
	v_sub_f32_e32 v74, v153, v122
	v_exp_f32_e32 v74, v74
	v_mov_b32_e32 v153, v122
	v_mul_f32_e32 v155, v155, v74
	v_mul_f32_e32 v24, v24, v74
	v_mul_f32_e32 v25, v25, v74
	v_mul_f32_e32 v22, v22, v74
	v_mul_f32_e32 v23, v23, v74
	v_mul_f32_e32 v20, v20, v74
	v_mul_f32_e32 v21, v21, v74
	v_mul_f32_e32 v18, v18, v74
	v_mul_f32_e32 v19, v19, v74
	v_mul_f32_e32 v16, v16, v74
	v_mul_f32_e32 v17, v17, v74
	v_mul_f32_e32 v14, v14, v74
	v_mul_f32_e32 v15, v15, v74
	v_mul_f32_e32 v12, v12, v74
	v_mul_f32_e32 v13, v13, v74
	v_mul_f32_e32 v11, v11, v74
	v_mul_f32_e32 v10, v10, v74
	s_branch .LBB0_261

.LBB0_260:
	v_mov_b32_e32 v122, v153
.LBB0_261:
	v_sub_f32_e32 v0, v0, v122
	v_exp_f32_e32 v0, v0
	v_sub_f32_e32 v1, v1, v122
	v_exp_f32_e32 v1, v1
	v_sub_f32_e32 v2, v2, v122
	v_exp_f32_e32 v2, v2
	v_sub_f32_e32 v3, v3, v122
	v_exp_f32_e32 v3, v3
	v_sub_f32_e32 v4, v4, v122
	v_add_f32_e32 v123, 0, v0
	v_exp_f32_e32 v4, v4
	v_sub_f32_e32 v5, v5, v122
	v_add_f32_e32 v123, v1, v123
	v_exp_f32_e32 v5, v5
	v_sub_f32_e32 v6, v6, v122
	v_add_f32_e32 v123, v2, v123
	v_exp_f32_e32 v6, v6
	v_sub_f32_e32 v7, v7, v122
	v_add_f32_e32 v123, v3, v123
	v_exp_f32_e32 v7, v7
	v_add_f32_e32 v123, v4, v123
	v_add_f32_e32 v123, v5, v123
	v_add_f32_e32 v123, v6, v123
	v_add_f32_e32 v122, v7, v123
	v_cvt_pk_bf16_f32 v126, v0, v1
	v_cvt_pk_bf16_f32 v127, v2, v3
	v_cvt_pk_bf16_f32 v128, v4, v5
	v_cvt_pk_bf16_f32 v129, v6, v7
	v_add_f32_e32 v155, v155, v122
	s_nop 0
	v_mfma_f32_16x16x32_bf16 v[0:3], v[54:57], v[126:129], v[22:25]
	v_mfma_f32_16x16x32_bf16 v[4:7], v[50:53], v[126:129], v[18:21]
	v_mfma_f32_16x16x32_bf16 v[122:125], v[46:49], v[126:129], v[14:17]
	v_mfma_f32_16x16x32_bf16 v[126:129], v[42:45], v[126:129], v[10:13]
